# SwiGLU K-loop: no LDS-DMA in 16-read load segments (4 in C-SP1, 2 in L-SP2, 2 in C-SP2)
# baseline (speedup 1.0000x reference)
.LBB0_628:
	s_ashr_i32 s13, s12, 31
	s_lshl_b64 s[6:7], s[12:13], 19
	s_add_u32 s6, s30, s6
	s_addc_u32 s7, s31, s7
	s_and_b64 s[24:25], s[38:39], exec
	s_cselect_b32 s13, s7, s35
	s_cselect_b32 s29, s6, s34
	s_ashr_i32 s5, s4, 31
	s_lshl_b64 s[24:25], s[4:5], 19
	s_add_u32 s24, s49, s24
	s_addc_u32 s25, s50, s25
	s_and_b64 s[42:43], s[38:39], exec
	s_cselect_b32 s5, s25, s41
	s_cselect_b32 s82, s24, s40
	s_add_u32 s34, s34, 0x40080
	s_addc_u32 s35, s35, 0
	s_add_u32 s83, s40, 0x100
	s_addc_u32 s84, s41, 0
	s_mov_b32 s85, -2
	s_add_u32 s40, s34, 0xfffc0080
	s_addc_u32 s41, s35, -1
	s_cmp_eq_u32 s85, 12
	s_cselect_b32 s43, s13, s41
	s_cselect_b32 s42, s29, s40
	s_cselect_b32 s41, s5, s84
	s_cselect_b32 s40, s82, s83
	s_add_u32 s86, s34, 0xfffc0000
	s_addc_u32 s87, s35, -1
	s_add_i32 s62, 0, 0x10000
	s_add_i32 s63, 0, 0x14000
	v_add_u32_e32 v152, s62, v172
	v_add_u32_e32 v158, s63, v172
	v_add_u32_e32 v245, s62, v243
	v_add_u32_e32 v246, s63, v243
	ds_read_b128 v[128:131], v152
	ds_read_b128 v[144:147], v245
	ds_read_b128 v[148:151], v152 offset:2048
	ds_read_b128 v[152:155], v245 offset:2048
	ds_read_b128 v[174:177], v158
	ds_read_b128 v[178:181], v246
	ds_read_b128 v[182:185], v158 offset:2048
	ds_read_b128 v[186:189], v246 offset:2048
	ds_read_b128 v[190:193], v173
	ds_read_b128 v[198:201], v244
	ds_read_b128 v[202:205], v173 offset:2048
	ds_read_b128 v[206:209], v244 offset:2048
	ds_read_b128 v[210:213], v173 offset:4096
	ds_read_b128 v[214:217], v244 offset:4096
	ds_read_b128 v[218:221], v173 offset:6144
	ds_read_b128 v[222:225], v244 offset:6144
	s_waitcnt vmcnt(4)
	s_waitcnt lgkmcnt(0)
	s_barrier
	s_setprio 1
	s_waitcnt lgkmcnt(0)
	v_mfma_f32_16x16x32_bf16 v[124:127], v[128:131], v[190:193], 0
	s_mov_b32 m0, s76
	v_mfma_f32_16x16x32_bf16 v[116:119], v[148:151], v[190:193], 0
	v_mfma_f32_16x16x32_bf16 v[108:111], v[128:131], v[202:205], 0
	global_load_lds_dwordx4 v132, s[86:87]
	v_mfma_f32_16x16x32_bf16 v[100:103], v[148:151], v[202:205], 0
	v_mfma_f32_16x16x32_bf16 v[92:95], v[128:131], v[210:213], 0
	s_mov_b32 m0, s77
	v_mfma_f32_16x16x32_bf16 v[84:87], v[148:151], v[210:213], 0
	v_mfma_f32_16x16x32_bf16 v[76:79], v[128:131], v[218:221], 0
	global_load_lds_dwordx4 v136, s[86:87]
	v_mfma_f32_16x16x32_bf16 v[68:71], v[148:151], v[218:221], 0
	v_mfma_f32_16x16x32_bf16 v[124:127], v[144:147], v[198:201], v[124:127]
	s_add_i32 m0, s51, 0xc000
	v_mfma_f32_16x16x32_bf16 v[116:119], v[152:155], v[198:201], v[116:119]
	v_mfma_f32_16x16x32_bf16 v[108:111], v[144:147], v[206:209], v[108:111]
	global_load_lds_dwordx4 v132, s[34:35]
	v_mfma_f32_16x16x32_bf16 v[100:103], v[152:155], v[206:209], v[100:103]
	v_mfma_f32_16x16x32_bf16 v[92:95], v[144:147], v[214:217], v[92:95]
	s_add_i32 m0, s51, 0xe000
	v_mfma_f32_16x16x32_bf16 v[84:87], v[152:155], v[214:217], v[84:87]
	v_mfma_f32_16x16x32_bf16 v[76:79], v[144:147], v[222:225], v[76:79]
	global_load_lds_dwordx4 v136, s[34:35]
	v_mfma_f32_16x16x32_bf16 v[68:71], v[152:155], v[222:225], v[68:71]
	s_setprio 0
	s_setprio 1
	v_mfma_f32_16x16x32_bf16 v[120:123], v[174:177], v[190:193], 0
	v_mfma_f32_16x16x32_bf16 v[112:115], v[182:185], v[190:193], 0
	v_mfma_f32_16x16x32_bf16 v[104:107], v[174:177], v[202:205], 0
	v_mfma_f32_16x16x32_bf16 v[96:99], v[182:185], v[202:205], 0
	v_mfma_f32_16x16x32_bf16 v[88:91], v[174:177], v[210:213], 0
	v_mfma_f32_16x16x32_bf16 v[80:83], v[182:185], v[210:213], 0
	v_mfma_f32_16x16x32_bf16 v[72:75], v[174:177], v[218:221], 0
	v_mfma_f32_16x16x32_bf16 v[64:67], v[182:185], v[218:221], 0
	v_mfma_f32_16x16x32_bf16 v[120:123], v[178:181], v[198:201], v[120:123]
	v_mfma_f32_16x16x32_bf16 v[112:115], v[186:189], v[198:201], v[112:115]
	v_mfma_f32_16x16x32_bf16 v[104:107], v[178:181], v[206:209], v[104:107]
	v_mfma_f32_16x16x32_bf16 v[96:99], v[186:189], v[206:209], v[96:99]
	v_mfma_f32_16x16x32_bf16 v[88:91], v[178:181], v[214:217], v[88:91]
	v_mfma_f32_16x16x32_bf16 v[80:83], v[186:189], v[214:217], v[80:83]
	v_mfma_f32_16x16x32_bf16 v[72:75], v[178:181], v[222:225], v[72:75]
	v_mfma_f32_16x16x32_bf16 v[64:67], v[186:189], v[222:225], v[64:67]
	s_setprio 0
	s_barrier
	s_add_i32 s62, s62, s48
	s_mov_b32 m0, s62
	ds_read_b128 v[190:193], v173 offset:16384
	global_load_lds_dwordx4 v134, s[40:41]
	s_add_i32 m0, s62, 0x2000
	ds_read_b128 v[198:201], v244 offset:16384
	global_load_lds_dwordx4 v138, s[40:41]
	ds_read_b128 v[202:205], v173 offset:18432
	ds_read_b128 v[206:209], v244 offset:18432
	ds_read_b128 v[210:213], v173 offset:20480
	ds_read_b128 v[214:217], v244 offset:20480
	ds_read_b128 v[218:221], v173 offset:22528
	ds_read_b128 v[222:225], v244 offset:22528
	s_add_u32 s86, s40, 0x40000
	s_addc_u32 s87, s41, 0
	s_add_i32 s62, s63, s48
	s_waitcnt vmcnt(4)
	s_waitcnt lgkmcnt(0)
	s_barrier
	s_setprio 1
	s_waitcnt lgkmcnt(0)
	v_mfma_f32_16x16x32_bf16 v[60:63], v[128:131], v[190:193], 0
	v_mfma_f32_16x16x32_bf16 v[52:55], v[148:151], v[190:193], 0
	v_mfma_f32_16x16x32_bf16 v[44:47], v[128:131], v[202:205], 0
	s_mov_b32 m0, s62
	v_mfma_f32_16x16x32_bf16 v[36:39], v[148:151], v[202:205], 0
	v_mfma_f32_16x16x32_bf16 v[28:31], v[128:131], v[210:213], 0
	global_load_lds_dwordx4 v134, s[86:87]
	v_mfma_f32_16x16x32_bf16 v[20:23], v[148:151], v[210:213], 0
	v_mfma_f32_16x16x32_bf16 v[8:11], v[128:131], v[218:221], 0
	v_mfma_f32_16x16x32_bf16 v[4:7], v[148:151], v[218:221], 0
	v_mfma_f32_16x16x32_bf16 v[60:63], v[144:147], v[198:201], v[60:63]
	v_mfma_f32_16x16x32_bf16 v[52:55], v[152:155], v[198:201], v[52:55]
	v_mfma_f32_16x16x32_bf16 v[44:47], v[144:147], v[206:209], v[44:47]
	s_add_i32 m0, s62, 0x2000
	v_mfma_f32_16x16x32_bf16 v[36:39], v[152:155], v[206:209], v[36:39]
	v_mfma_f32_16x16x32_bf16 v[28:31], v[144:147], v[214:217], v[28:31]
	global_load_lds_dwordx4 v138, s[86:87]
	v_mfma_f32_16x16x32_bf16 v[20:23], v[152:155], v[214:217], v[20:23]
	v_mfma_f32_16x16x32_bf16 v[8:11], v[144:147], v[222:225], v[8:11]
	v_mfma_f32_16x16x32_bf16 v[4:7], v[152:155], v[222:225], v[4:7]
	s_setprio 0
	s_setprio 1
	v_mfma_f32_16x16x32_bf16 v[56:59], v[174:177], v[190:193], 0
	v_mfma_f32_16x16x32_bf16 v[48:51], v[182:185], v[190:193], 0
	v_mfma_f32_16x16x32_bf16 v[40:43], v[174:177], v[202:205], 0
	v_mfma_f32_16x16x32_bf16 v[32:35], v[182:185], v[202:205], 0
	v_mfma_f32_16x16x32_bf16 v[24:27], v[174:177], v[210:213], 0
	v_mfma_f32_16x16x32_bf16 v[16:19], v[182:185], v[210:213], 0
	v_mfma_f32_16x16x32_bf16 v[12:15], v[174:177], v[218:221], 0
	v_mfma_f32_16x16x32_bf16 v[0:3], v[182:185], v[218:221], 0
	v_mfma_f32_16x16x32_bf16 v[56:59], v[178:181], v[198:201], v[56:59]
	v_mfma_f32_16x16x32_bf16 v[48:51], v[186:189], v[198:201], v[48:51]
	v_mfma_f32_16x16x32_bf16 v[40:43], v[178:181], v[206:209], v[40:43]
	v_mfma_f32_16x16x32_bf16 v[32:35], v[186:189], v[206:209], v[32:35]
	v_mfma_f32_16x16x32_bf16 v[24:27], v[178:181], v[214:217], v[24:27]
	v_mfma_f32_16x16x32_bf16 v[16:19], v[186:189], v[214:217], v[16:19]
	v_mfma_f32_16x16x32_bf16 v[12:15], v[178:181], v[222:225], v[12:15]
	v_mfma_f32_16x16x32_bf16 v[0:3], v[186:189], v[222:225], v[0:3]
	s_setprio 0
	s_barrier
	s_add_i32 s62, 0, 0x18000
	s_add_i32 s63, 0, 0x1c000
	v_add_u32_e32 v152, s62, v172
	v_add_u32_e32 v158, s63, v172
	v_add_u32_e32 v245, s62, v243
	v_add_u32_e32 v246, s63, v243
	ds_read_b128 v[128:131], v152
	ds_read_b128 v[144:147], v245
	ds_read_b128 v[148:151], v152 offset:2048
	ds_read_b128 v[152:155], v245 offset:2048
	ds_read_b128 v[174:177], v158
	ds_read_b128 v[178:181], v246
	ds_read_b128 v[182:185], v158 offset:2048
	ds_read_b128 v[186:189], v246 offset:2048
	ds_read_b128 v[190:193], v173 offset:32768
	ds_read_b128 v[198:201], v244 offset:32768
	ds_read_b128 v[202:205], v173 offset:34816
	ds_read_b128 v[206:209], v244 offset:34816
	ds_read_b128 v[210:213], v173 offset:36864
	ds_read_b128 v[214:217], v244 offset:36864
	ds_read_b128 v[218:221], v173 offset:38912
	ds_read_b128 v[222:225], v244 offset:38912
	s_add_u32 s88, s42, 0x40000
	s_addc_u32 s89, s43, 0
	s_waitcnt vmcnt(4)
	s_waitcnt lgkmcnt(0)
	s_barrier
	s_setprio 1
	s_waitcnt lgkmcnt(0)
	v_mfma_f32_16x16x32_bf16 v[124:127], v[128:131], v[190:193], v[124:127]
	s_mov_b32 m0, s51
	v_mfma_f32_16x16x32_bf16 v[116:119], v[148:151], v[190:193], v[116:119]
	v_mfma_f32_16x16x32_bf16 v[108:111], v[128:131], v[202:205], v[108:111]
	global_load_lds_dwordx4 v132, s[42:43]
	v_mfma_f32_16x16x32_bf16 v[100:103], v[148:151], v[202:205], v[100:103]
	v_mfma_f32_16x16x32_bf16 v[92:95], v[128:131], v[210:213], v[92:95]
	s_mov_b32 m0, s60
	v_mfma_f32_16x16x32_bf16 v[84:87], v[148:151], v[210:213], v[84:87]
	v_mfma_f32_16x16x32_bf16 v[76:79], v[128:131], v[218:221], v[76:79]
	global_load_lds_dwordx4 v136, s[42:43]
	v_mfma_f32_16x16x32_bf16 v[68:71], v[148:151], v[218:221], v[68:71]
	v_mfma_f32_16x16x32_bf16 v[124:127], v[144:147], v[198:201], v[124:127]
	s_mov_b32 m0, s61
	v_mfma_f32_16x16x32_bf16 v[116:119], v[152:155], v[198:201], v[116:119]
	v_mfma_f32_16x16x32_bf16 v[108:111], v[144:147], v[206:209], v[108:111]
	global_load_lds_dwordx4 v132, s[88:89]
	v_mfma_f32_16x16x32_bf16 v[100:103], v[152:155], v[206:209], v[100:103]
	v_mfma_f32_16x16x32_bf16 v[92:95], v[144:147], v[214:217], v[92:95]
	s_mov_b32 m0, s64
	v_mfma_f32_16x16x32_bf16 v[84:87], v[152:155], v[214:217], v[84:87]
	v_mfma_f32_16x16x32_bf16 v[76:79], v[144:147], v[222:225], v[76:79]
	global_load_lds_dwordx4 v136, s[88:89]
	v_mfma_f32_16x16x32_bf16 v[68:71], v[152:155], v[222:225], v[68:71]
	s_setprio 0
	s_setprio 1
	v_mfma_f32_16x16x32_bf16 v[120:123], v[174:177], v[190:193], v[120:123]
	v_mfma_f32_16x16x32_bf16 v[112:115], v[182:185], v[190:193], v[112:115]
	v_mfma_f32_16x16x32_bf16 v[104:107], v[174:177], v[202:205], v[104:107]
	v_mfma_f32_16x16x32_bf16 v[96:99], v[182:185], v[202:205], v[96:99]
	v_mfma_f32_16x16x32_bf16 v[88:91], v[174:177], v[210:213], v[88:91]
	v_mfma_f32_16x16x32_bf16 v[80:83], v[182:185], v[210:213], v[80:83]
	v_mfma_f32_16x16x32_bf16 v[72:75], v[174:177], v[218:221], v[72:75]
	v_mfma_f32_16x16x32_bf16 v[64:67], v[182:185], v[218:221], v[64:67]
	v_mfma_f32_16x16x32_bf16 v[120:123], v[178:181], v[198:201], v[120:123]
	v_mfma_f32_16x16x32_bf16 v[112:115], v[186:189], v[198:201], v[112:115]
	v_mfma_f32_16x16x32_bf16 v[104:107], v[178:181], v[206:209], v[104:107]
	v_mfma_f32_16x16x32_bf16 v[96:99], v[186:189], v[206:209], v[96:99]
	v_mfma_f32_16x16x32_bf16 v[88:91], v[178:181], v[214:217], v[88:91]
	v_mfma_f32_16x16x32_bf16 v[80:83], v[186:189], v[214:217], v[80:83]
	v_mfma_f32_16x16x32_bf16 v[72:75], v[178:181], v[222:225], v[72:75]
	v_mfma_f32_16x16x32_bf16 v[64:67], v[186:189], v[222:225], v[64:67]
	s_setprio 0
	s_barrier
	s_add_i32 s42, s62, s48
	s_add_u32 s40, s40, 0x80
	s_addc_u32 s41, s41, 0
	s_mov_b32 m0, s42
	ds_read_b128 v[190:193], v173 offset:49152
	global_load_lds_dwordx4 v134, s[40:41]
	s_add_i32 m0, s42, 0x2000
	ds_read_b128 v[198:201], v244 offset:49152
	global_load_lds_dwordx4 v138, s[40:41]
	ds_read_b128 v[202:205], v173 offset:51200
	ds_read_b128 v[206:209], v244 offset:51200
	ds_read_b128 v[210:213], v173 offset:53248
	ds_read_b128 v[214:217], v244 offset:53248
	ds_read_b128 v[218:221], v173 offset:55296
	ds_read_b128 v[222:225], v244 offset:55296
	s_add_u32 s40, s40, 0x40000
	s_addc_u32 s41, s41, 0
	s_add_i32 s42, s63, s48
	s_waitcnt vmcnt(4)
	s_waitcnt lgkmcnt(0)
	s_barrier
	s_setprio 1
	s_waitcnt lgkmcnt(0)
	v_mfma_f32_16x16x32_bf16 v[60:63], v[128:131], v[190:193], v[60:63]
	v_mfma_f32_16x16x32_bf16 v[52:55], v[148:151], v[190:193], v[52:55]
	v_mfma_f32_16x16x32_bf16 v[44:47], v[128:131], v[202:205], v[44:47]
	s_mov_b32 m0, s42
	v_mfma_f32_16x16x32_bf16 v[36:39], v[148:151], v[202:205], v[36:39]
	v_mfma_f32_16x16x32_bf16 v[28:31], v[128:131], v[210:213], v[28:31]
	global_load_lds_dwordx4 v134, s[40:41]
	v_mfma_f32_16x16x32_bf16 v[20:23], v[148:151], v[210:213], v[20:23]
	v_mfma_f32_16x16x32_bf16 v[8:11], v[128:131], v[218:221], v[8:11]
	v_mfma_f32_16x16x32_bf16 v[4:7], v[148:151], v[218:221], v[4:7]
	v_mfma_f32_16x16x32_bf16 v[60:63], v[144:147], v[198:201], v[60:63]
	v_mfma_f32_16x16x32_bf16 v[52:55], v[152:155], v[198:201], v[52:55]
	v_mfma_f32_16x16x32_bf16 v[44:47], v[144:147], v[206:209], v[44:47]
	s_add_i32 m0, s42, 0x2000
	v_mfma_f32_16x16x32_bf16 v[36:39], v[152:155], v[206:209], v[36:39]
	v_mfma_f32_16x16x32_bf16 v[28:31], v[144:147], v[214:217], v[28:31]
	global_load_lds_dwordx4 v138, s[40:41]
	v_mfma_f32_16x16x32_bf16 v[20:23], v[152:155], v[214:217], v[20:23]
	v_mfma_f32_16x16x32_bf16 v[8:11], v[144:147], v[222:225], v[8:11]
	v_mfma_f32_16x16x32_bf16 v[4:7], v[152:155], v[222:225], v[4:7]
	s_setprio 0
	s_setprio 1
	v_mfma_f32_16x16x32_bf16 v[56:59], v[174:177], v[190:193], v[56:59]
	v_mfma_f32_16x16x32_bf16 v[48:51], v[182:185], v[190:193], v[48:51]
	v_mfma_f32_16x16x32_bf16 v[40:43], v[174:177], v[202:205], v[40:43]
	v_mfma_f32_16x16x32_bf16 v[32:35], v[182:185], v[202:205], v[32:35]
	v_mfma_f32_16x16x32_bf16 v[24:27], v[174:177], v[210:213], v[24:27]
	v_mfma_f32_16x16x32_bf16 v[16:19], v[182:185], v[210:213], v[16:19]
	v_mfma_f32_16x16x32_bf16 v[12:15], v[174:177], v[218:221], v[12:15]
	v_mfma_f32_16x16x32_bf16 v[0:3], v[182:185], v[218:221], v[0:3]
	v_mfma_f32_16x16x32_bf16 v[56:59], v[178:181], v[198:201], v[56:59]
	v_mfma_f32_16x16x32_bf16 v[48:51], v[186:189], v[198:201], v[48:51]
	v_mfma_f32_16x16x32_bf16 v[40:43], v[178:181], v[206:209], v[40:43]
	v_mfma_f32_16x16x32_bf16 v[32:35], v[186:189], v[206:209], v[32:35]
	v_mfma_f32_16x16x32_bf16 v[24:27], v[178:181], v[214:217], v[24:27]
	v_mfma_f32_16x16x32_bf16 v[16:19], v[186:189], v[214:217], v[16:19]
	v_mfma_f32_16x16x32_bf16 v[12:15], v[178:181], v[222:225], v[12:15]
	v_mfma_f32_16x16x32_bf16 v[0:3], v[186:189], v[222:225], v[0:3]
	s_setprio 0
	s_barrier
	s_add_i32 s85, s85, 2
	s_add_u32 s34, s34, 0x100
	s_addc_u32 s35, s35, 0
	s_add_u32 s83, s83, 0x100
	s_addc_u32 s84, s84, 0
.LBB0_629:
	s_add_u32 s40, s34, 0xfffc0080
	s_addc_u32 s41, s35, -1
	s_cmp_eq_u32 s85, 12
	s_cselect_b32 s43, s13, s41
	s_cselect_b32 s42, s29, s40
	s_cselect_b32 s41, s5, s84
	s_cselect_b32 s40, s82, s83
	s_add_u32 s86, s34, 0xfffc0000
	s_addc_u32 s87, s35, -1
	s_add_i32 s62, 0, 0x10000
	s_add_i32 s63, 0, 0x14000
	v_add_u32_e32 v152, s62, v172
	v_add_u32_e32 v158, s63, v172
	v_add_u32_e32 v245, s62, v243
	v_add_u32_e32 v246, s63, v243
	ds_read_b128 v[128:131], v152
	ds_read_b128 v[144:147], v245
	ds_read_b128 v[148:151], v152 offset:2048
	ds_read_b128 v[152:155], v245 offset:2048
	ds_read_b128 v[174:177], v158
	ds_read_b128 v[178:181], v246
	ds_read_b128 v[182:185], v158 offset:2048
	ds_read_b128 v[186:189], v246 offset:2048
	ds_read_b128 v[190:193], v173
	ds_read_b128 v[198:201], v244
	ds_read_b128 v[202:205], v173 offset:2048
	ds_read_b128 v[206:209], v244 offset:2048
	ds_read_b128 v[210:213], v173 offset:4096
	ds_read_b128 v[214:217], v244 offset:4096
	ds_read_b128 v[218:221], v173 offset:6144
	ds_read_b128 v[222:225], v244 offset:6144
	s_waitcnt vmcnt(4)
	s_waitcnt lgkmcnt(0)
	s_barrier
	s_setprio 1
	s_waitcnt lgkmcnt(0)
	v_mfma_f32_16x16x32_bf16 v[124:127], v[128:131], v[190:193], v[124:127]
	s_mov_b32 m0, s76
	v_mfma_f32_16x16x32_bf16 v[116:119], v[148:151], v[190:193], v[116:119]
	v_mfma_f32_16x16x32_bf16 v[108:111], v[128:131], v[202:205], v[108:111]
	global_load_lds_dwordx4 v132, s[86:87]
	v_mfma_f32_16x16x32_bf16 v[100:103], v[148:151], v[202:205], v[100:103]
	v_mfma_f32_16x16x32_bf16 v[92:95], v[128:131], v[210:213], v[92:95]
	s_mov_b32 m0, s77
	v_mfma_f32_16x16x32_bf16 v[84:87], v[148:151], v[210:213], v[84:87]
	v_mfma_f32_16x16x32_bf16 v[76:79], v[128:131], v[218:221], v[76:79]
	global_load_lds_dwordx4 v136, s[86:87]
	v_mfma_f32_16x16x32_bf16 v[68:71], v[148:151], v[218:221], v[68:71]
	v_mfma_f32_16x16x32_bf16 v[124:127], v[144:147], v[198:201], v[124:127]
	s_add_i32 m0, s51, 0xc000
	v_mfma_f32_16x16x32_bf16 v[116:119], v[152:155], v[198:201], v[116:119]
	v_mfma_f32_16x16x32_bf16 v[108:111], v[144:147], v[206:209], v[108:111]
	global_load_lds_dwordx4 v132, s[34:35]
	v_mfma_f32_16x16x32_bf16 v[100:103], v[152:155], v[206:209], v[100:103]
	v_mfma_f32_16x16x32_bf16 v[92:95], v[144:147], v[214:217], v[92:95]
	s_add_i32 m0, s51, 0xe000
	v_mfma_f32_16x16x32_bf16 v[84:87], v[152:155], v[214:217], v[84:87]
	v_mfma_f32_16x16x32_bf16 v[76:79], v[144:147], v[222:225], v[76:79]
	global_load_lds_dwordx4 v136, s[34:35]
	v_mfma_f32_16x16x32_bf16 v[68:71], v[152:155], v[222:225], v[68:71]
	s_setprio 0
	s_setprio 1
	v_mfma_f32_16x16x32_bf16 v[120:123], v[174:177], v[190:193], v[120:123]
	v_mfma_f32_16x16x32_bf16 v[112:115], v[182:185], v[190:193], v[112:115]
	v_mfma_f32_16x16x32_bf16 v[104:107], v[174:177], v[202:205], v[104:107]
	v_mfma_f32_16x16x32_bf16 v[96:99], v[182:185], v[202:205], v[96:99]
	v_mfma_f32_16x16x32_bf16 v[88:91], v[174:177], v[210:213], v[88:91]
	v_mfma_f32_16x16x32_bf16 v[80:83], v[182:185], v[210:213], v[80:83]
	v_mfma_f32_16x16x32_bf16 v[72:75], v[174:177], v[218:221], v[72:75]
	v_mfma_f32_16x16x32_bf16 v[64:67], v[182:185], v[218:221], v[64:67]
	v_mfma_f32_16x16x32_bf16 v[120:123], v[178:181], v[198:201], v[120:123]
	v_mfma_f32_16x16x32_bf16 v[112:115], v[186:189], v[198:201], v[112:115]
	v_mfma_f32_16x16x32_bf16 v[104:107], v[178:181], v[206:209], v[104:107]
	v_mfma_f32_16x16x32_bf16 v[96:99], v[186:189], v[206:209], v[96:99]
	v_mfma_f32_16x16x32_bf16 v[88:91], v[178:181], v[214:217], v[88:91]
	v_mfma_f32_16x16x32_bf16 v[80:83], v[186:189], v[214:217], v[80:83]
	v_mfma_f32_16x16x32_bf16 v[72:75], v[178:181], v[222:225], v[72:75]
	v_mfma_f32_16x16x32_bf16 v[64:67], v[186:189], v[222:225], v[64:67]
	s_setprio 0
	s_barrier
	s_add_i32 s62, s62, s48
	s_mov_b32 m0, s62
	ds_read_b128 v[190:193], v173 offset:16384
	global_load_lds_dwordx4 v134, s[40:41]
	s_add_i32 m0, s62, 0x2000
	ds_read_b128 v[198:201], v244 offset:16384
	global_load_lds_dwordx4 v138, s[40:41]
	ds_read_b128 v[202:205], v173 offset:18432
	ds_read_b128 v[206:209], v244 offset:18432
	ds_read_b128 v[210:213], v173 offset:20480
	ds_read_b128 v[214:217], v244 offset:20480
	ds_read_b128 v[218:221], v173 offset:22528
	ds_read_b128 v[222:225], v244 offset:22528
	s_add_u32 s86, s40, 0x40000
	s_addc_u32 s87, s41, 0
	s_add_i32 s62, s63, s48
	s_waitcnt vmcnt(4)
	s_waitcnt lgkmcnt(0)
	s_barrier
	s_setprio 1
	s_waitcnt lgkmcnt(0)
	v_mfma_f32_16x16x32_bf16 v[60:63], v[128:131], v[190:193], v[60:63]
	v_mfma_f32_16x16x32_bf16 v[52:55], v[148:151], v[190:193], v[52:55]
	v_mfma_f32_16x16x32_bf16 v[44:47], v[128:131], v[202:205], v[44:47]
	s_mov_b32 m0, s62
	v_mfma_f32_16x16x32_bf16 v[36:39], v[148:151], v[202:205], v[36:39]
	v_mfma_f32_16x16x32_bf16 v[28:31], v[128:131], v[210:213], v[28:31]
	global_load_lds_dwordx4 v134, s[86:87]
	v_mfma_f32_16x16x32_bf16 v[20:23], v[148:151], v[210:213], v[20:23]
	v_mfma_f32_16x16x32_bf16 v[8:11], v[128:131], v[218:221], v[8:11]
	v_mfma_f32_16x16x32_bf16 v[4:7], v[148:151], v[218:221], v[4:7]
	v_mfma_f32_16x16x32_bf16 v[60:63], v[144:147], v[198:201], v[60:63]
	v_mfma_f32_16x16x32_bf16 v[52:55], v[152:155], v[198:201], v[52:55]
	v_mfma_f32_16x16x32_bf16 v[44:47], v[144:147], v[206:209], v[44:47]
	s_add_i32 m0, s62, 0x2000
	v_mfma_f32_16x16x32_bf16 v[36:39], v[152:155], v[206:209], v[36:39]
	v_mfma_f32_16x16x32_bf16 v[28:31], v[144:147], v[214:217], v[28:31]
	global_load_lds_dwordx4 v138, s[86:87]
	v_mfma_f32_16x16x32_bf16 v[20:23], v[152:155], v[214:217], v[20:23]
	v_mfma_f32_16x16x32_bf16 v[8:11], v[144:147], v[222:225], v[8:11]
	v_mfma_f32_16x16x32_bf16 v[4:7], v[152:155], v[222:225], v[4:7]
	s_setprio 0
	s_setprio 1
	v_mfma_f32_16x16x32_bf16 v[56:59], v[174:177], v[190:193], v[56:59]
	v_mfma_f32_16x16x32_bf16 v[48:51], v[182:185], v[190:193], v[48:51]
	v_mfma_f32_16x16x32_bf16 v[40:43], v[174:177], v[202:205], v[40:43]
	v_mfma_f32_16x16x32_bf16 v[32:35], v[182:185], v[202:205], v[32:35]
	v_mfma_f32_16x16x32_bf16 v[24:27], v[174:177], v[210:213], v[24:27]
	v_mfma_f32_16x16x32_bf16 v[16:19], v[182:185], v[210:213], v[16:19]
	v_mfma_f32_16x16x32_bf16 v[12:15], v[174:177], v[218:221], v[12:15]
	v_mfma_f32_16x16x32_bf16 v[0:3], v[182:185], v[218:221], v[0:3]
	v_mfma_f32_16x16x32_bf16 v[56:59], v[178:181], v[198:201], v[56:59]
	v_mfma_f32_16x16x32_bf16 v[48:51], v[186:189], v[198:201], v[48:51]
	v_mfma_f32_16x16x32_bf16 v[40:43], v[178:181], v[206:209], v[40:43]
	v_mfma_f32_16x16x32_bf16 v[32:35], v[186:189], v[206:209], v[32:35]
	v_mfma_f32_16x16x32_bf16 v[24:27], v[178:181], v[214:217], v[24:27]
	v_mfma_f32_16x16x32_bf16 v[16:19], v[186:189], v[214:217], v[16:19]
	v_mfma_f32_16x16x32_bf16 v[12:15], v[178:181], v[222:225], v[12:15]
	v_mfma_f32_16x16x32_bf16 v[0:3], v[186:189], v[222:225], v[0:3]
	s_setprio 0
	s_barrier
	s_add_i32 s62, 0, 0x18000
	s_add_i32 s63, 0, 0x1c000
	v_add_u32_e32 v152, s62, v172
	v_add_u32_e32 v158, s63, v172
	v_add_u32_e32 v245, s62, v243
	v_add_u32_e32 v246, s63, v243
	ds_read_b128 v[128:131], v152
	ds_read_b128 v[144:147], v245
	ds_read_b128 v[148:151], v152 offset:2048
	ds_read_b128 v[152:155], v245 offset:2048
	ds_read_b128 v[174:177], v158
	ds_read_b128 v[178:181], v246
	ds_read_b128 v[182:185], v158 offset:2048
	ds_read_b128 v[186:189], v246 offset:2048
	ds_read_b128 v[190:193], v173 offset:32768
	ds_read_b128 v[198:201], v244 offset:32768
	ds_read_b128 v[202:205], v173 offset:34816
	ds_read_b128 v[206:209], v244 offset:34816
	ds_read_b128 v[210:213], v173 offset:36864
	ds_read_b128 v[214:217], v244 offset:36864
	ds_read_b128 v[218:221], v173 offset:38912
	ds_read_b128 v[222:225], v244 offset:38912
	s_add_u32 s88, s42, 0x40000
	s_addc_u32 s89, s43, 0
	s_waitcnt vmcnt(4)
	s_waitcnt lgkmcnt(0)
	s_barrier
	s_setprio 1
	s_waitcnt lgkmcnt(0)
	v_mfma_f32_16x16x32_bf16 v[124:127], v[128:131], v[190:193], v[124:127]
	s_mov_b32 m0, s51
	v_mfma_f32_16x16x32_bf16 v[116:119], v[148:151], v[190:193], v[116:119]
	v_mfma_f32_16x16x32_bf16 v[108:111], v[128:131], v[202:205], v[108:111]
	global_load_lds_dwordx4 v132, s[42:43]
	v_mfma_f32_16x16x32_bf16 v[100:103], v[148:151], v[202:205], v[100:103]
	v_mfma_f32_16x16x32_bf16 v[92:95], v[128:131], v[210:213], v[92:95]
	s_mov_b32 m0, s60
	v_mfma_f32_16x16x32_bf16 v[84:87], v[148:151], v[210:213], v[84:87]
	v_mfma_f32_16x16x32_bf16 v[76:79], v[128:131], v[218:221], v[76:79]
	global_load_lds_dwordx4 v136, s[42:43]
	v_mfma_f32_16x16x32_bf16 v[68:71], v[148:151], v[218:221], v[68:71]
	v_mfma_f32_16x16x32_bf16 v[124:127], v[144:147], v[198:201], v[124:127]
	s_mov_b32 m0, s61
	v_mfma_f32_16x16x32_bf16 v[116:119], v[152:155], v[198:201], v[116:119]
	v_mfma_f32_16x16x32_bf16 v[108:111], v[144:147], v[206:209], v[108:111]
	global_load_lds_dwordx4 v132, s[88:89]
	v_mfma_f32_16x16x32_bf16 v[100:103], v[152:155], v[206:209], v[100:103]
	v_mfma_f32_16x16x32_bf16 v[92:95], v[144:147], v[214:217], v[92:95]
	s_mov_b32 m0, s64
	v_mfma_f32_16x16x32_bf16 v[84:87], v[152:155], v[214:217], v[84:87]
	v_mfma_f32_16x16x32_bf16 v[76:79], v[144:147], v[222:225], v[76:79]
	global_load_lds_dwordx4 v136, s[88:89]
	v_mfma_f32_16x16x32_bf16 v[68:71], v[152:155], v[222:225], v[68:71]
	s_setprio 0
	s_setprio 1
	v_mfma_f32_16x16x32_bf16 v[120:123], v[174:177], v[190:193], v[120:123]
	v_mfma_f32_16x16x32_bf16 v[112:115], v[182:185], v[190:193], v[112:115]
	v_mfma_f32_16x16x32_bf16 v[104:107], v[174:177], v[202:205], v[104:107]
	v_mfma_f32_16x16x32_bf16 v[96:99], v[182:185], v[202:205], v[96:99]
	v_mfma_f32_16x16x32_bf16 v[88:91], v[174:177], v[210:213], v[88:91]
	v_mfma_f32_16x16x32_bf16 v[80:83], v[182:185], v[210:213], v[80:83]
	v_mfma_f32_16x16x32_bf16 v[72:75], v[174:177], v[218:221], v[72:75]
	v_mfma_f32_16x16x32_bf16 v[64:67], v[182:185], v[218:221], v[64:67]
	v_mfma_f32_16x16x32_bf16 v[120:123], v[178:181], v[198:201], v[120:123]
	v_mfma_f32_16x16x32_bf16 v[112:115], v[186:189], v[198:201], v[112:115]
	v_mfma_f32_16x16x32_bf16 v[104:107], v[178:181], v[206:209], v[104:107]
	v_mfma_f32_16x16x32_bf16 v[96:99], v[186:189], v[206:209], v[96:99]
	v_mfma_f32_16x16x32_bf16 v[88:91], v[178:181], v[214:217], v[88:91]
	v_mfma_f32_16x16x32_bf16 v[80:83], v[186:189], v[214:217], v[80:83]
	v_mfma_f32_16x16x32_bf16 v[72:75], v[178:181], v[222:225], v[72:75]
	v_mfma_f32_16x16x32_bf16 v[64:67], v[186:189], v[222:225], v[64:67]
	s_setprio 0
	s_barrier
	s_add_i32 s42, s62, s48
	s_add_u32 s40, s40, 0x80
	s_addc_u32 s41, s41, 0
	s_mov_b32 m0, s42
	ds_read_b128 v[190:193], v173 offset:49152
	global_load_lds_dwordx4 v134, s[40:41]
	s_add_i32 m0, s42, 0x2000
	ds_read_b128 v[198:201], v244 offset:49152
	global_load_lds_dwordx4 v138, s[40:41]
	ds_read_b128 v[202:205], v173 offset:51200
	ds_read_b128 v[206:209], v244 offset:51200
	ds_read_b128 v[210:213], v173 offset:53248
	ds_read_b128 v[214:217], v244 offset:53248
	ds_read_b128 v[218:221], v173 offset:55296
	ds_read_b128 v[222:225], v244 offset:55296
	s_add_u32 s40, s40, 0x40000
	s_addc_u32 s41, s41, 0
	s_add_i32 s42, s63, s48
	s_waitcnt vmcnt(4)
	s_waitcnt lgkmcnt(0)
	s_barrier
	s_setprio 1
	s_waitcnt lgkmcnt(0)
	v_mfma_f32_16x16x32_bf16 v[60:63], v[128:131], v[190:193], v[60:63]
	v_mfma_f32_16x16x32_bf16 v[52:55], v[148:151], v[190:193], v[52:55]
	v_mfma_f32_16x16x32_bf16 v[44:47], v[128:131], v[202:205], v[44:47]
	s_mov_b32 m0, s42
	v_mfma_f32_16x16x32_bf16 v[36:39], v[148:151], v[202:205], v[36:39]
	v_mfma_f32_16x16x32_bf16 v[28:31], v[128:131], v[210:213], v[28:31]
	global_load_lds_dwordx4 v134, s[40:41]
	v_mfma_f32_16x16x32_bf16 v[20:23], v[148:151], v[210:213], v[20:23]
	v_mfma_f32_16x16x32_bf16 v[8:11], v[128:131], v[218:221], v[8:11]
	v_mfma_f32_16x16x32_bf16 v[4:7], v[148:151], v[218:221], v[4:7]
	v_mfma_f32_16x16x32_bf16 v[60:63], v[144:147], v[198:201], v[60:63]
	v_mfma_f32_16x16x32_bf16 v[52:55], v[152:155], v[198:201], v[52:55]
	v_mfma_f32_16x16x32_bf16 v[44:47], v[144:147], v[206:209], v[44:47]
	s_add_i32 m0, s42, 0x2000
	v_mfma_f32_16x16x32_bf16 v[36:39], v[152:155], v[206:209], v[36:39]
	v_mfma_f32_16x16x32_bf16 v[28:31], v[144:147], v[214:217], v[28:31]
	global_load_lds_dwordx4 v138, s[40:41]
	v_mfma_f32_16x16x32_bf16 v[20:23], v[152:155], v[214:217], v[20:23]
	v_mfma_f32_16x16x32_bf16 v[8:11], v[144:147], v[222:225], v[8:11]
	v_mfma_f32_16x16x32_bf16 v[4:7], v[152:155], v[222:225], v[4:7]
	s_setprio 0
	s_setprio 1
	v_mfma_f32_16x16x32_bf16 v[56:59], v[174:177], v[190:193], v[56:59]
	v_mfma_f32_16x16x32_bf16 v[48:51], v[182:185], v[190:193], v[48:51]
	v_mfma_f32_16x16x32_bf16 v[40:43], v[174:177], v[202:205], v[40:43]
	v_mfma_f32_16x16x32_bf16 v[32:35], v[182:185], v[202:205], v[32:35]
	v_mfma_f32_16x16x32_bf16 v[24:27], v[174:177], v[210:213], v[24:27]
	v_mfma_f32_16x16x32_bf16 v[16:19], v[182:185], v[210:213], v[16:19]
	v_mfma_f32_16x16x32_bf16 v[12:15], v[174:177], v[218:221], v[12:15]
	v_mfma_f32_16x16x32_bf16 v[0:3], v[182:185], v[218:221], v[0:3]
	v_mfma_f32_16x16x32_bf16 v[56:59], v[178:181], v[198:201], v[56:59]
	v_mfma_f32_16x16x32_bf16 v[48:51], v[186:189], v[198:201], v[48:51]
	v_mfma_f32_16x16x32_bf16 v[40:43], v[178:181], v[206:209], v[40:43]
	v_mfma_f32_16x16x32_bf16 v[32:35], v[186:189], v[206:209], v[32:35]
	v_mfma_f32_16x16x32_bf16 v[24:27], v[178:181], v[214:217], v[24:27]
	v_mfma_f32_16x16x32_bf16 v[16:19], v[186:189], v[214:217], v[16:19]
	v_mfma_f32_16x16x32_bf16 v[12:15], v[178:181], v[222:225], v[12:15]
	v_mfma_f32_16x16x32_bf16 v[0:3], v[186:189], v[222:225], v[0:3]
	s_setprio 0
	s_barrier
	s_add_i32 s85, s85, 2
	s_add_u32 s34, s34, 0x100
	s_addc_u32 s35, s35, 0
	s_add_u32 s83, s83, 0x100
	s_addc_u32 s84, s84, 0
	s_cmp_gt_u32 s85, 13
	s_cbranch_scc0 .LBB0_629
	s_and_b64 vcc, exec, s[2:3]
	s_cbranch_vccz .LBB0_632
	s_barrier
